# attention softmax: cross-lane max / sum through v_permlane16_swap / v_permlane32_swap instead of four ds_bpermute round trips per query tile
# baseline (speedup 1.0000x reference)
; #define LAS __attribute__((address_space(3)))
; __device__ __forceinline__ void attn_phase(LAS unsigned char* lds, const bf16_t* QKVZ, const float* sinks, bf16_t* OG, int G, int bid, int tid) {
;     ...
;         for (int mt = 0; mt < 4; ++mt) {
;             const int qo0 = qh * 64 + mt * 16;
;             const size_t row = (size_t)(b * T + n * 128 + qo0 + fr);
;             const bf16_t* qp = QKVZ + row * ATT_IN + h * 64 + fq * 8;
;             const bf16x8 q0 = *(const bf16x8*)qp, q1 = *(const bf16x8*)(qp + 32);
;             const int kt0 = (qh * 4 + mt) < 6 ? (qh * 4 + mt) : 6;
;             f32x4 s[10];
; #pragma unroll
;             for (int kt = 0; kt < 10; ++kt) {
;                 const LAS unsigned char* kp = Kl + ((kt0 + kt) * 16 + fr) * KP + fq * 16;
;                 const bf16x8 k0 = *(const LAS bf16x8*)kp, k1 = *(const LAS bf16x8*)(kp + 64);
;                 f32x4 acc = (f32x4){0.f, 0.f, 0.f, 0.f};
;                 acc = __builtin_amdgcn_mfma_f32_16x16x32_bf16(k0, q0, acc, 0, 0, 0);
;                 acc = __builtin_amdgcn_mfma_f32_16x16x32_bf16(k1, q1, acc, 0, 0, 0);
;                 s[kt] = acc;
;             }
.Lmy_att_t0:
	v_add_u32_e32 v82, s1, v140
	v_mov_b64_e32 v[32:33], s[14:15]
	v_mad_i64_i32 v[84:85], s[26:27], v82, s22, v[32:33]
	v_lshl_add_u64 v[36:37], v[84:85], 0, v[72:73]
	v_mov_b64_e32 v[32:33], v[186:187]
	v_mov_b64_e32 v[34:35], v[188:189]
	v_mov_b64_e32 v[162:163], v[190:191]
	v_mov_b64_e32 v[164:165], v[192:193]
	s_mov_b32 s99, 0x14000
	s_cmp_eq_u32 s1, 48
	s_cselect_b32 s99, 0x27c4000, s99
	v_add_co_u32_e32 v194, vcc, s99, v36
	s_nop 1
	v_addc_co_u32_e32 v195, vcc, 0, v37, vcc
	global_load_dwordx4 v[186:189], v[194:195], off
	global_load_dwordx4 v[190:193], v[194:195], off offset:64
	v_lshlrev_b32_e32 v196, 1, v76
	v_mov_b32_e32 v197, v73
	v_lshl_add_u64 v[198:199], v[84:85], 0, v[196:197]
	global_load_dwordx2 v[200:201], v[198:199], off offset:3072
	global_load_dwordx2 v[202:203], v[198:199], off offset:3104
	global_load_dwordx2 v[204:205], v[198:199], off offset:3136
	global_load_dwordx2 v[206:207], v[198:199], off offset:3168
	s_min_u32 s25, s8, 6
	s_lshl_b32 s25, s25, 4
	s_add_i32 s26, s25, 16
	s_add_i32 s29, s25, 32
	s_add_i32 s28, s25, 64
	s_add_i32 s27, s25, 0x60
	s_add_i32 s30, s25, 0x90
	s_add_i32 s26, s25, 48
	s_add_i32 s26, s25, 0x50
	s_add_i32 s26, s25, 0x70
	s_or_b32 s26, s25, 0x80
	v_or_b32_e32 v248, s25, v89
	v_mad_u32_u24 v248, v248, s19, v90
	ds_read_b128 v[208:211], v248
	ds_read_b128 v[212:215], v248 offset:64
	ds_read_b128 v[216:219], v248 offset:2304
	ds_read_b128 v[220:223], v248 offset:2368
	ds_read_b128 v[224:227], v248 offset:4608
	ds_read_b128 v[228:231], v248 offset:4672
	ds_read_b128 v[232:235], v248 offset:6912
	ds_read_b128 v[236:239], v248 offset:6976
	ds_read_b128 v[240:243], v248 offset:9216
	ds_read_b128 v[244:247], v248 offset:9280
	v_subrev_u32_e32 v185, s25, v129
	v_add_u32_e32 v146, s25, v139
	v_subrev_u32_e32 v180, s25, v118
	v_subrev_u32_e32 v179, s25, v117
	v_subrev_u32_e32 v184, s25, v128
	v_subrev_u32_e32 v178, s25, v116
	v_subrev_u32_e32 v175, s25, v107
	v_subrev_u32_e32 v183, s25, v127
	v_subrev_u32_e32 v177, s25, v115
	v_subrev_u32_e32 v174, s25, v106
	v_subrev_u32_e32 v182, s25, v126
	v_subrev_u32_e32 v176, s25, v114
	v_subrev_u32_e32 v161, s25, v105
	v_subrev_u32_e32 v181, s25, v125
	v_subrev_u32_e32 v159, s25, v113
	v_subrev_u32_e32 v158, s25, v104
	v_subrev_u32_e32 v160, s25, v124
	v_subrev_u32_e32 v156, s25, v112
	v_subrev_u32_e32 v155, s25, v103
	v_subrev_u32_e32 v157, s25, v123
	v_subrev_u32_e32 v152, s25, v111
	v_subrev_u32_e32 v151, s25, v102
	v_subrev_u32_e32 v153, s25, v122
	v_subrev_u32_e32 v149, s25, v110
	v_subrev_u32_e32 v147, s25, v101
	v_subrev_u32_e32 v150, s25, v121
	v_subrev_u32_e32 v145, s25, v109
	v_subrev_u32_e32 v144, s25, v100
	v_subrev_u32_e32 v148, s25, v120
	v_subrev_u32_e32 v143, s25, v108
	v_subrev_u32_e32 v142, s25, v98
	v_ashrrev_i32_e32 v83, 31, v82
	v_add_u32_e32 v139, -16, v139
	s_waitcnt lgkmcnt(8)
	v_mfma_f32_16x16x32_bf16 v[68:71], v[208:211], v[32:35], 0
	v_mfma_f32_16x16x32_bf16 v[68:71], v[212:215], v[162:165], v[68:71]
	s_waitcnt lgkmcnt(6)
	v_mfma_f32_16x16x32_bf16 v[64:67], v[216:219], v[32:35], 0
	v_mfma_f32_16x16x32_bf16 v[64:67], v[220:223], v[162:165], v[64:67]
	ds_read_b128 v[208:211], v248 offset:11520
	ds_read_b128 v[212:215], v248 offset:11584
	s_waitcnt lgkmcnt(6)
	v_mfma_f32_16x16x32_bf16 v[60:63], v[224:227], v[32:35], 0
	v_mfma_f32_16x16x32_bf16 v[60:63], v[228:231], v[162:165], v[60:63]
	ds_read_b128 v[216:219], v248 offset:13824
	ds_read_b128 v[220:223], v248 offset:13888
	s_waitcnt lgkmcnt(6)
	v_mfma_f32_16x16x32_bf16 v[56:59], v[232:235], v[32:35], 0
	v_mfma_f32_16x16x32_bf16 v[56:59], v[236:239], v[162:165], v[56:59]
	ds_read_b128 v[224:227], v248 offset:16128
	ds_read_b128 v[228:231], v248 offset:16192
	s_waitcnt lgkmcnt(6)
	v_mfma_f32_16x16x32_bf16 v[52:55], v[240:243], v[32:35], 0
	v_mfma_f32_16x16x32_bf16 v[52:55], v[244:247], v[162:165], v[52:55]
	ds_read_b128 v[232:235], v248 offset:18432
	ds_read_b128 v[236:239], v248 offset:18496
	s_waitcnt lgkmcnt(6)
	v_mfma_f32_16x16x32_bf16 v[48:51], v[208:211], v[32:35], 0
	v_mfma_f32_16x16x32_bf16 v[48:51], v[212:215], v[162:165], v[48:51]
	ds_read_b128 v[240:243], v248 offset:20736
	ds_read_b128 v[244:247], v248 offset:20800
	s_waitcnt lgkmcnt(6)
	v_mfma_f32_16x16x32_bf16 v[44:47], v[216:219], v[32:35], 0
	v_mfma_f32_16x16x32_bf16 v[44:47], v[220:223], v[162:165], v[44:47]
	s_waitcnt lgkmcnt(4)
	v_mfma_f32_16x16x32_bf16 v[40:43], v[224:227], v[32:35], 0
	v_mfma_f32_16x16x32_bf16 v[40:43], v[228:231], v[162:165], v[40:43]
	s_waitcnt lgkmcnt(2)
	v_mfma_f32_16x16x32_bf16 v[36:39], v[232:235], v[32:35], 0
	v_mfma_f32_16x16x32_bf16 v[36:39], v[236:239], v[162:165], v[36:39]
	s_waitcnt lgkmcnt(0)
; __device__ __forceinline__ void attn_phase(LAS unsigned char* lds, const bf16_t* QKVZ, const float* sinks, bf16_t* OG, int G, int bid, int tid) {
;     ...
;             float mx = sink2;
; #pragma unroll
;             for (int kt = 0; kt < 10; ++kt)
; #pragma unroll
;                 for (int r = 0; r < 4; ++r) { const int si = (kt0 + kt) * 16 + 4 * fq + r, df = qi - si; const bool ok = (df >= 0) && (df < 128) && (n > 0 || si >= 128);
;                     const float v = ok ? s[kt][r] : -1e30f; s[kt][r] = v; mx = fmaxf(mx, v); }
;             mx = fmaxf(mx, __shfl_xor(mx, 16)); mx = fmaxf(mx, __shfl_xor(mx, 32));
	v_mfma_f32_16x16x32_bf16 v[32:35], v[240:243], v[32:35], 0
	v_mfma_f32_16x16x32_bf16 v[32:35], v[244:247], v[162:165], v[32:35]
	v_or_b32_e32 v154, s25, v76
	v_add_u32_e32 v162, s1, v99
	v_add_u32_e32 v163, v162, v185
	v_cmp_gt_u32_e32 vcc, s20, v163
	s_and_b64 vcc, s[12:13], vcc
	v_add_u32_e32 v163, 0xffffff80, v146
	v_cndmask_b32_e32 v68, v138, v68, vcc
	v_cmp_lt_u32_e32 vcc, s23, v163
	s_and_b64 vcc, s[12:13], vcc
	v_add_u32_e32 v164, v162, v180
	v_cndmask_b32_e32 v69, v138, v69, vcc
	v_cmp_gt_u32_e32 vcc, s20, v164
	s_and_b64 vcc, s[12:13], vcc
	v_add_u32_e32 v164, v162, v179
	v_cndmask_b32_e32 v70, v138, v70, vcc
	v_cmp_gt_u32_e32 vcc, s20, v164
	s_and_b64 vcc, s[12:13], vcc
	v_add_u32_e32 v164, v162, v184
	v_cndmask_b32_e32 v71, v138, v71, vcc
	v_cmp_gt_u32_e32 vcc, s20, v164
	s_and_b64 vcc, s[12:13], vcc
	v_add_u32_e32 v164, 0xffffff90, v146
	v_cndmask_b32_e32 v64, v138, v64, vcc
	v_cmp_lt_u32_e32 vcc, s23, v164
	s_and_b64 vcc, s[12:13], vcc
	v_add_u32_e32 v164, v162, v178
	v_cndmask_b32_e32 v65, v138, v65, vcc
	v_cmp_gt_u32_e32 vcc, s20, v164
	s_and_b64 vcc, s[12:13], vcc
	v_add_u32_e32 v164, v162, v175
	v_cndmask_b32_e32 v66, v138, v66, vcc
	v_cmp_gt_u32_e32 vcc, s20, v164
	s_and_b64 vcc, s[12:13], vcc
	s_cmp_gt_u32 s8, 5
	v_add_u32_e32 v165, v162, v183
	s_cselect_b64 s[30:31], -1, 0
	v_cndmask_b32_e32 v67, v138, v67, vcc
	v_cmp_gt_u32_e32 vcc, s20, v165
	s_or_b64 s[30:31], s[12:13], s[30:31]
	s_and_b64 vcc, vcc, s[30:31]
	v_add_u32_e32 v165, 0xffffffa0, v146
	v_cndmask_b32_e32 v60, v138, v60, vcc
	v_cmp_lt_u32_e32 vcc, s23, v165
	s_and_b64 vcc, vcc, s[30:31]
	v_add_u32_e32 v165, v162, v177
	v_cndmask_b32_e32 v61, v138, v61, vcc
	v_cmp_gt_u32_e32 vcc, s20, v165
	s_and_b64 vcc, vcc, s[30:31]
	v_add_u32_e32 v165, v162, v174
	v_cndmask_b32_e32 v62, v138, v62, vcc
	v_cmp_gt_u32_e32 vcc, s20, v165
	s_and_b64 vcc, vcc, s[30:31]
	s_cmp_gt_u32 s8, 4
	v_add_u32_e32 v165, v162, v182
	s_cselect_b64 s[30:31], -1, 0
	v_cndmask_b32_e32 v63, v138, v63, vcc
	v_cmp_gt_u32_e32 vcc, s20, v165
	s_or_b64 s[30:31], s[12:13], s[30:31]
	s_and_b64 vcc, vcc, s[30:31]
	v_add_u32_e32 v165, 0xffffffb0, v146
	v_cndmask_b32_e32 v56, v138, v56, vcc
	v_cmp_lt_u32_e32 vcc, s23, v165
	s_and_b64 vcc, vcc, s[30:31]
	v_add_u32_e32 v165, v162, v176
	v_cndmask_b32_e32 v57, v138, v57, vcc
	v_cmp_gt_u32_e32 vcc, s20, v165
	s_and_b64 vcc, vcc, s[30:31]
	v_add_u32_e32 v161, v162, v161
	v_cndmask_b32_e32 v58, v138, v58, vcc
	v_cmp_gt_u32_e32 vcc, s20, v161
	s_and_b64 vcc, vcc, s[30:31]
	s_cmp_gt_u32 s8, 3
	v_add_u32_e32 v165, v162, v181
	s_cselect_b64 s[30:31], -1, 0
	v_cndmask_b32_e32 v59, v138, v59, vcc
	v_cmp_gt_u32_e32 vcc, s20, v165
	s_or_b64 s[30:31], s[12:13], s[30:31]
	s_and_b64 vcc, vcc, s[30:31]
	v_subrev_u32_e32 v165, 64, v146
	v_cndmask_b32_e32 v52, v138, v52, vcc
	v_cmp_lt_u32_e32 vcc, s23, v165
	s_and_b64 vcc, vcc, s[30:31]
	v_add_u32_e32 v159, v162, v159
	v_cndmask_b32_e32 v53, v138, v53, vcc
	v_cmp_gt_u32_e32 vcc, s20, v159
	s_and_b64 vcc, vcc, s[30:31]
	v_add_u32_e32 v158, v162, v158
	v_cndmask_b32_e32 v54, v138, v54, vcc
	v_cmp_gt_u32_e32 vcc, s20, v158
	s_and_b64 vcc, vcc, s[30:31]
	s_cmp_gt_u32 s8, 2
	v_add_u32_e32 v159, v162, v160
	s_cselect_b64 s[30:31], -1, 0
	v_cndmask_b32_e32 v55, v138, v55, vcc
	v_cmp_gt_u32_e32 vcc, s20, v159
	s_or_b64 s[30:31], s[12:13], s[30:31]
	s_and_b64 vcc, vcc, s[30:31]
	v_subrev_u32_e32 v159, 48, v146
	v_cndmask_b32_e32 v48, v138, v48, vcc
	v_cmp_lt_u32_e32 vcc, s23, v159
	s_and_b64 vcc, vcc, s[30:31]
	v_add_u32_e32 v156, v162, v156
	v_cndmask_b32_e32 v49, v138, v49, vcc
	v_cmp_gt_u32_e32 vcc, s20, v156
	s_and_b64 vcc, vcc, s[30:31]
	v_add_u32_e32 v155, v162, v155
	v_cndmask_b32_e32 v50, v138, v50, vcc
	v_cmp_gt_u32_e32 vcc, s20, v155
	s_and_b64 vcc, vcc, s[30:31]
	s_cmp_gt_u32 s8, 1
	v_add_u32_e32 v157, v162, v157
	s_cselect_b64 s[30:31], -1, 0
	v_cndmask_b32_e32 v51, v138, v51, vcc
	v_cmp_gt_u32_e32 vcc, s20, v157
	s_or_b64 s[30:31], s[12:13], s[30:31]
	s_and_b64 vcc, vcc, s[30:31]
	v_subrev_u32_e32 v157, 32, v146
	v_cndmask_b32_e32 v44, v138, v44, vcc
	v_cmp_lt_u32_e32 vcc, s23, v157
	s_and_b64 vcc, vcc, s[30:31]
	v_add_u32_e32 v152, v162, v152
	v_cndmask_b32_e32 v45, v138, v45, vcc
	v_cmp_gt_u32_e32 vcc, s20, v152
	s_and_b64 vcc, vcc, s[30:31]
	v_add_u32_e32 v151, v162, v151
	v_cndmask_b32_e32 v46, v138, v46, vcc
	v_cmp_gt_u32_e32 vcc, s20, v151
	v_max3_f32 v163, v141, v68, v69
	s_and_b64 vcc, vcc, s[30:31]
	s_or_b32 s30, s8, s0
	v_max3_f32 v163, v163, v70, v71
	v_add_u32_e32 v152, v162, v153
	s_cmp_lg_u32 s30, 0
	v_max3_f32 v163, v163, v64, v65
	v_cndmask_b32_e32 v47, v138, v47, vcc
	v_cmp_gt_u32_e32 vcc, s20, v152
	s_cselect_b64 s[30:31], -1, 0
	v_max3_f32 v163, v163, v66, v67
	s_and_b64 vcc, s[30:31], vcc
	v_add_u32_e32 v152, -16, v146
	v_max3_f32 v163, v163, v60, v61
	v_cndmask_b32_e32 v40, v138, v40, vcc
	v_cmp_lt_u32_e32 vcc, s23, v152
	v_max3_f32 v163, v163, v62, v63
	s_and_b64 vcc, s[30:31], vcc
	v_add_u32_e32 v149, v162, v149
	v_max3_f32 v163, v163, v56, v57
	v_cndmask_b32_e32 v41, v138, v41, vcc
	v_cmp_gt_u32_e32 vcc, s20, v149
	v_max3_f32 v161, v163, v58, v59
	s_and_b64 vcc, s[30:31], vcc
	v_add_u32_e32 v147, v162, v147
	v_max3_f32 v161, v161, v52, v53
	v_cndmask_b32_e32 v42, v138, v42, vcc
	v_cmp_gt_u32_e32 vcc, s20, v147
	v_max3_f32 v158, v161, v54, v55
	s_and_b64 vcc, s[30:31], vcc
	v_add_u32_e32 v150, v162, v150
	v_max3_f32 v158, v158, v48, v49
	v_cndmask_b32_e32 v43, v138, v43, vcc
	v_cmp_gt_u32_e32 vcc, s20, v150
	v_max3_f32 v155, v158, v50, v51
	v_add_u32_e32 v145, v162, v145
	v_cndmask_b32_e32 v36, v138, v36, vcc
	v_cmp_lt_u32_e32 vcc, s23, v146
	v_max3_f32 v155, v155, v44, v45
	v_add_u32_e32 v144, v162, v144
	v_cndmask_b32_e32 v37, v138, v37, vcc
	v_cmp_gt_u32_e32 vcc, s20, v145
	v_max3_f32 v151, v155, v46, v47
	v_add_u32_e32 v145, v162, v148
	v_cndmask_b32_e32 v38, v138, v38, vcc
	v_cmp_gt_u32_e32 vcc, s20, v144
	v_max3_f32 v151, v151, v40, v41
	v_max3_f32 v147, v151, v42, v43
	v_cndmask_b32_e32 v39, v138, v39, vcc
	v_cmp_gt_u32_e32 vcc, s20, v145
	v_add_u32_e32 v145, 16, v146
	v_add_u32_e32 v143, v162, v143
	v_cndmask_b32_e32 v32, v138, v32, vcc
	v_cmp_lt_u32_e32 vcc, s23, v145
	v_max3_f32 v147, v147, v36, v37
	v_add_u32_e32 v142, v162, v142
	v_cndmask_b32_e32 v33, v138, v33, vcc
	v_cmp_gt_u32_e32 vcc, s20, v143
	v_max3_f32 v144, v147, v38, v39
	v_max3_f32 v144, v144, v32, v33
	v_cndmask_b32_e32 v34, v138, v34, vcc
	v_cmp_gt_u32_e32 vcc, s20, v142
	v_or_b32_e32 v164, s29, v76
	v_or_b32_e32 v163, s28, v76
	v_cndmask_b32_e32 v35, v138, v35, vcc
	v_max3_f32 v142, v144, v34, v35
	v_mov_b32_e32 v143, v142
	s_nop 1
	v_permlane16_swap_b32_e32 v142, v143
	v_or_b32_e32 v156, s27, v76
	v_or_b32_e32 v149, s26, v76
	s_add_i32 s1, s1, 16
	s_add_i32 s8, s8, 1
	s_waitcnt lgkmcnt(0)
; __device__ __forceinline__ u32x4 pack8(const f32x4 a, const f32x4 b) { u32x4 w; w.x = cvt_pk_bf16(a[0], a[1]); w.y = cvt_pk_bf16(a[2], a[3]); w.z = cvt_pk_bf16(b[0], b[1]); w.w = cvt_pk_bf16(b[2], b[3]); return w; }
; #define LAS __attribute__((address_space(3)))
; __device__ __forceinline__ void attn_phase(LAS unsigned char* lds, const bf16_t* QKVZ, const float* sinks, bf16_t* OG, int G, int bid, int tid) {
;     ...
;             mx = fmaxf(mx, __shfl_xor(mx, 16)); mx = fmaxf(mx, __shfl_xor(mx, 32));
;             float sum = 0.f;
; #pragma unroll
;             for (int kt = 0; kt < 10; ++kt)
; #pragma unroll
;                 for (int r = 0; r < 4; ++r) { const float p = __builtin_amdgcn_exp2f(s[kt][r] - mx); s[kt][r] = p; sum += p; }
;             sum += __shfl_xor(sum, 16); sum += __shfl_xor(sum, 32);
;             sum += __builtin_amdgcn_exp2f(sink2 - mx);
;             const float inv = 1.0f / sum;
;             f32x4 o[4];
; #pragma unroll
;             for (int dt = 0; dt < 4; ++dt) o[dt] = (f32x4){0.f, 0.f, 0.f, 0.f};
; #pragma unroll
;             for (int kk = 0; kk < 5; ++kk) {
;                 const u32x4 pw = pack8(s[2 * kk], s[2 * kk + 1]);
;                 const bf16x8 pf = __builtin_bit_cast(bf16x8, pw);
; #pragma unroll
;                 for (int dt = 0; dt < 4; ++dt) {
;                     const int d = dt * 16 + fr, sw = ((d >> 3) & 7) << 2, keyA = 16 * (kt0 + 2 * kk) + 4 * fq, keyB = keyA + 16;
;                     const u32x2 va = *(const LAS u32x2*)(Vt + d * VP + ((keyA ^ sw) * 2)), vb = *(const LAS u32x2*)(Vt + d * VP + ((keyB ^ sw) * 2));
	v_max_f32_e32 v143, v143, v143
	v_max_f32_e32 v142, v142, v143
	v_mov_b32_e32 v143, v142
	s_nop 1
	v_permlane32_swap_b32_e32 v142, v143
	s_cmp_eq_u32 s1, 64
	s_waitcnt lgkmcnt(0)
	v_max_f32_e32 v143, v143, v143
	v_max_f32_e32 v142, v142, v143
	v_sub_f32_e32 v68, v68, v142
	v_exp_f32_e32 v68, v68
	v_sub_f32_e32 v69, v69, v142
	v_exp_f32_e32 v69, v69
	v_sub_f32_e32 v70, v70, v142
	v_exp_f32_e32 v70, v70
	v_sub_f32_e32 v71, v71, v142
	v_exp_f32_e32 v71, v71
	v_sub_f32_e32 v64, v64, v142
	v_add_f32_e32 v143, 0, v68
	v_exp_f32_e32 v64, v64
	v_sub_f32_e32 v65, v65, v142
	v_add_f32_e32 v143, v69, v143
	v_exp_f32_e32 v65, v65
	v_sub_f32_e32 v66, v66, v142
	v_add_f32_e32 v143, v70, v143
	v_exp_f32_e32 v66, v66
	v_sub_f32_e32 v67, v67, v142
	v_add_f32_e32 v143, v71, v143
	v_exp_f32_e32 v67, v67
	v_sub_f32_e32 v60, v60, v142
	v_add_f32_e32 v143, v64, v143
	v_exp_f32_e32 v60, v60
	v_sub_f32_e32 v61, v61, v142
	v_add_f32_e32 v143, v65, v143
	v_exp_f32_e32 v61, v61
	v_sub_f32_e32 v62, v62, v142
	v_add_f32_e32 v143, v66, v143
	v_exp_f32_e32 v62, v62
	v_sub_f32_e32 v63, v63, v142
	v_add_f32_e32 v143, v67, v143
	v_exp_f32_e32 v63, v63
	v_sub_f32_e32 v56, v56, v142
	v_add_f32_e32 v143, v60, v143
	v_exp_f32_e32 v56, v56
	v_sub_f32_e32 v57, v57, v142
	v_add_f32_e32 v143, v61, v143
	v_exp_f32_e32 v57, v57
	v_sub_f32_e32 v58, v58, v142
	v_add_f32_e32 v143, v62, v143
	v_exp_f32_e32 v58, v58
	v_sub_f32_e32 v59, v59, v142
	v_add_f32_e32 v143, v63, v143
	v_exp_f32_e32 v59, v59
	v_sub_f32_e32 v52, v52, v142
	v_add_f32_e32 v143, v56, v143
	v_exp_f32_e32 v144, v52
	v_add_f32_e32 v143, v57, v143
	v_add_f32_e32 v143, v58, v143
	v_add_f32_e32 v143, v59, v143
	v_sub_f32_e32 v53, v53, v142
	v_add_f32_e32 v52, v144, v143
	v_exp_f32_e32 v143, v53
	v_sub_f32_e32 v53, v54, v142
	v_exp_f32_e32 v145, v53
	v_sub_f32_e32 v53, v55, v142
	v_exp_f32_e32 v146, v53
	v_sub_f32_e32 v48, v48, v142
	v_exp_f32_e32 v147, v48
	v_sub_f32_e32 v49, v49, v142
	v_add_f32_e32 v52, v143, v52
	v_exp_f32_e32 v148, v49
	v_sub_f32_e32 v49, v50, v142
	v_add_f32_e32 v52, v145, v52
	v_exp_f32_e32 v150, v49
	v_sub_f32_e32 v49, v51, v142
	v_add_f32_e32 v52, v146, v52
	v_exp_f32_e32 v151, v49
	v_sub_f32_e32 v44, v44, v142
	v_add_f32_e32 v48, v147, v52
	v_exp_f32_e32 v152, v44
	v_sub_f32_e32 v45, v45, v142
	v_add_f32_e32 v48, v148, v48
	v_exp_f32_e32 v153, v45
	v_sub_f32_e32 v45, v46, v142
	v_add_f32_e32 v48, v150, v48
	v_exp_f32_e32 v155, v45
	v_sub_f32_e32 v45, v47, v142
	v_add_f32_e32 v48, v151, v48
	v_exp_f32_e32 v157, v45
	v_sub_f32_e32 v40, v40, v142
	v_add_f32_e32 v44, v152, v48
	v_exp_f32_e32 v158, v40
	v_sub_f32_e32 v41, v41, v142
	v_add_f32_e32 v44, v153, v44
	v_exp_f32_e32 v159, v41
	v_sub_f32_e32 v41, v42, v142
	v_add_f32_e32 v44, v155, v44
	v_exp_f32_e32 v160, v41
	v_sub_f32_e32 v41, v43, v142
	v_add_f32_e32 v44, v157, v44
	v_exp_f32_e32 v161, v41
	v_sub_f32_e32 v36, v36, v142
	v_add_f32_e32 v40, v158, v44
	v_exp_f32_e32 v162, v36
	v_sub_f32_e32 v37, v37, v142
	v_add_f32_e32 v40, v159, v40
	v_exp_f32_e32 v165, v37
	v_sub_f32_e32 v37, v38, v142
	v_add_f32_e32 v40, v160, v40
	v_exp_f32_e32 v166, v37
	v_sub_f32_e32 v37, v39, v142
	v_add_f32_e32 v40, v161, v40
	v_exp_f32_e32 v167, v37
	v_sub_f32_e32 v32, v32, v142
	v_add_f32_e32 v36, v162, v40
	v_exp_f32_e32 v168, v32
	v_sub_f32_e32 v33, v33, v142
	v_add_f32_e32 v36, v165, v36
	v_exp_f32_e32 v169, v33
	v_sub_f32_e32 v33, v34, v142
	v_add_f32_e32 v36, v166, v36
	v_exp_f32_e32 v170, v33
	v_sub_f32_e32 v33, v35, v142
	v_add_f32_e32 v36, v167, v36
	v_exp_f32_e32 v171, v33
	v_add_f32_e32 v32, v168, v36
	v_add_f32_e32 v32, v169, v32
	v_add_f32_e32 v32, v170, v32
	v_add_f32_e32 v32, v171, v32
	v_mov_b32_e32 v33, v32
	s_nop 1
	v_permlane16_swap_b32_e32 v32, v33
	v_add_u32_e32 v50, 16, v154
	v_bitop3_b32 v36, s25, v93, v76 bitop3:0x36
	v_xor_b32_e32 v38, v50, v93
	v_bitop3_b32 v40, s25, v95, v76 bitop3:0x36
	s_waitcnt lgkmcnt(0)
	v_add_f32_e32 v32, v32, v33
	v_mov_b32_e32 v33, v32
	s_nop 1
	v_permlane32_swap_b32_e32 v32, v33
	v_xor_b32_e32 v42, v50, v95
	v_bitop3_b32 v44, s25, v96, v76 bitop3:0x36
	v_xor_b32_e32 v46, v50, v96
	v_bitop3_b32 v48, s25, v97, v76 bitop3:0x36
	s_waitcnt lgkmcnt(0)
	v_add_f32_e32 v32, v32, v33
	v_sub_f32_e32 v33, v141, v142
	v_exp_f32_e32 v33, v33
	v_xor_b32_e32 v50, v50, v97
	v_lshl_add_u32 v36, v36, 1, v94
	v_lshl_add_u32 v38, v38, 1, v94
	v_lshl_add_u32 v40, v40, 1, v94
	v_lshl_add_u32 v42, v42, 1, v94
	v_lshl_add_u32 v44, v44, 1, v94
	v_lshl_add_u32 v46, v46, 1, v94
	v_lshl_add_u32 v48, v48, 1, v94
	v_lshl_add_u32 v50, v50, 1, v94
	v_mov_b32_e32 v208, v36
	v_mov_b32_e32 v209, v38
	v_mov_b32_e32 v210, v40
	v_mov_b32_e32 v211, v42
	v_mov_b32_e32 v212, v44
	v_mov_b32_e32 v213, v46
	v_mov_b32_e32 v214, v48
	v_mov_b32_e32 v215, v50
	v_add_f32_e32 v142, v33, v32
	v_cvt_pk_bf16_f32 v32, v68, v69
	v_cvt_pk_bf16_f32 v33, v70, v71
	v_cvt_pk_bf16_f32 v34, v64, v65
	v_cvt_pk_bf16_f32 v35, v66, v67
	ds_read_b64 v[36:37], v36 offset:36864
	ds_read_b64 v[38:39], v38 offset:36864
	ds_read_b64 v[40:41], v40 offset:45312
	ds_read_b64 v[42:43], v42 offset:45312
	ds_read_b64 v[44:45], v44 offset:53760
	ds_read_b64 v[46:47], v46 offset:53760
	ds_read_b64 v[48:49], v48 offset:62208
	ds_read_b64 v[50:51], v50 offset:62208
	ds_read_b64 v[232:233], v208 offset:36928
	ds_read_b64 v[234:235], v209 offset:36928
	ds_read_b64 v[236:237], v210 offset:45376
	ds_read_b64 v[238:239], v211 offset:45376
	ds_read_b64 v[240:241], v212 offset:53824
	ds_read_b64 v[242:243], v213 offset:53824
	ds_read_b64 v[244:245], v214 offset:62272
	ds_read_b64 v[246:247], v215 offset:62272
	s_waitcnt lgkmcnt(14)
; __device__ __forceinline__ u32x4 pack8(const f32x4 a, const f32x4 b) { u32x4 w; w.x = cvt_pk_bf16(a[0], a[1]); w.y = cvt_pk_bf16(a[2], a[3]); w.z = cvt_pk_bf16(b[0], b[1]); w.w = cvt_pk_bf16(b[2], b[3]); return w; }
; #define LAS __attribute__((address_space(3)))
; __device__ __forceinline__ void attn_phase(LAS unsigned char* lds, const bf16_t* QKVZ, const float* sinks, bf16_t* OG, int G, int bid, int tid) {
;     ...
;             const float inv = 1.0f / sum;
;             f32x4 o[4];
; #pragma unroll
;             for (int dt = 0; dt < 4; ++dt) o[dt] = (f32x4){0.f, 0.f, 0.f, 0.f};
; #pragma unroll
;             for (int kk = 0; kk < 5; ++kk) {
;                 const u32x4 pw = pack8(s[2 * kk], s[2 * kk + 1]);
;                 const bf16x8 pf = __builtin_bit_cast(bf16x8, pw);
; #pragma unroll
;                 for (int dt = 0; dt < 4; ++dt) {
;                     const int d = dt * 16 + fr, sw = ((d >> 3) & 7) << 2, keyA = 16 * (kt0 + 2 * kk) + 4 * fq, keyB = keyA + 16;
;                     const u32x2 va = *(const LAS u32x2*)(Vt + d * VP + ((keyA ^ sw) * 2)), vb = *(const LAS u32x2*)(Vt + d * VP + ((keyB ^ sw) * 2));
;                     const u32x4 vw = (u32x4){va.x, va.y, vb.x, vb.y};
;                     o[dt] = __builtin_amdgcn_mfma_f32_16x16x32_bf16(__builtin_bit_cast(bf16x8, vw), pf, o[dt], 0, 0, 0);
;                 }
;             }
	v_mfma_f32_16x16x32_bf16 v[36:39], v[36:39], v[32:35], 0
	v_bitop3_b32 v52, s29, v93, v76 bitop3:0x36
	v_lshl_add_u32 v52, v52, 1, v94
	s_waitcnt lgkmcnt(12)
	v_mfma_f32_16x16x32_bf16 v[40:43], v[40:43], v[32:35], 0
	s_waitcnt lgkmcnt(10)
	v_mfma_f32_16x16x32_bf16 v[44:47], v[44:47], v[32:35], 0
	s_waitcnt lgkmcnt(8)
	v_mfma_f32_16x16x32_bf16 v[32:35], v[48:51], v[32:35], 0
	v_cvt_pk_bf16_f32 v48, v60, v61
	v_cvt_pk_bf16_f32 v49, v62, v63
	v_cvt_pk_bf16_f32 v50, v56, v57
	v_cvt_pk_bf16_f32 v51, v58, v59
	s_nop 1
	ds_read_b64 v[216:217], v208 offset:36992
	ds_read_b64 v[218:219], v209 offset:36992
	ds_read_b64 v[220:221], v210 offset:45440
	ds_read_b64 v[222:223], v211 offset:45440
	ds_read_b64 v[224:225], v212 offset:53888
	ds_read_b64 v[226:227], v213 offset:53888
	ds_read_b64 v[228:229], v214 offset:62336
	ds_read_b64 v[230:231], v215 offset:62336
	s_waitcnt lgkmcnt(8)
	v_mfma_f32_16x16x32_bf16 v[36:39], v[232:235], v[48:51], v[36:39]
	v_mfma_f32_16x16x32_bf16 v[40:43], v[236:239], v[48:51], v[40:43]
	v_mfma_f32_16x16x32_bf16 v[44:47], v[240:243], v[48:51], v[44:47]
	v_mfma_f32_16x16x32_bf16 v[32:35], v[244:247], v[48:51], v[32:35]
	v_cvt_pk_bf16_f32 v248, v144, v143
	v_cvt_pk_bf16_f32 v249, v145, v146
	v_cvt_pk_bf16_f32 v250, v147, v148
	v_cvt_pk_bf16_f32 v251, v150, v151
	s_nop 1
	ds_read_b64 v[232:233], v208 offset:37056
	ds_read_b64 v[234:235], v209 offset:37056
	ds_read_b64 v[236:237], v210 offset:45504
	ds_read_b64 v[238:239], v211 offset:45504
	ds_read_b64 v[240:241], v212 offset:53952
	ds_read_b64 v[242:243], v213 offset:53952
	ds_read_b64 v[244:245], v214 offset:62400
	ds_read_b64 v[246:247], v215 offset:62400
	s_waitcnt lgkmcnt(8)
	v_mfma_f32_16x16x32_bf16 v[36:39], v[216:219], v[248:251], v[36:39]
	v_mfma_f32_16x16x32_bf16 v[40:43], v[220:223], v[248:251], v[40:43]
	v_mfma_f32_16x16x32_bf16 v[44:47], v[224:227], v[248:251], v[44:47]
	v_mfma_f32_16x16x32_bf16 v[32:35], v[228:231], v[248:251], v[32:35]
	v_cvt_pk_bf16_f32 v48, v152, v153
	v_cvt_pk_bf16_f32 v49, v155, v157
	v_cvt_pk_bf16_f32 v50, v158, v159
	v_cvt_pk_bf16_f32 v51, v160, v161
	s_nop 1
	ds_read_b64 v[216:217], v208 offset:37120
	ds_read_b64 v[218:219], v209 offset:37120
	ds_read_b64 v[220:221], v210 offset:45568
	ds_read_b64 v[222:223], v211 offset:45568
	ds_read_b64 v[224:225], v212 offset:54016
	ds_read_b64 v[226:227], v213 offset:54016
	ds_read_b64 v[228:229], v214 offset:62464
	ds_read_b64 v[230:231], v215 offset:62464
	s_waitcnt lgkmcnt(8)
	v_mfma_f32_16x16x32_bf16 v[36:39], v[232:235], v[48:51], v[36:39]
	v_mfma_f32_16x16x32_bf16 v[40:43], v[236:239], v[48:51], v[40:43]
	v_mfma_f32_16x16x32_bf16 v[52:55], v[240:243], v[48:51], v[44:47]
	v_mfma_f32_16x16x32_bf16 v[32:35], v[244:247], v[48:51], v[32:35]
	v_cvt_pk_bf16_f32 v248, v162, v165
	v_cvt_pk_bf16_f32 v249, v166, v167
	v_cvt_pk_bf16_f32 v250, v168, v169
	v_cvt_pk_bf16_f32 v251, v170, v171
	s_nop 1
	s_waitcnt lgkmcnt(0)
	v_mfma_f32_16x16x32_bf16 v[44:47], v[216:219], v[248:251], v[36:39]
	v_mfma_f32_16x16x32_bf16 v[40:43], v[220:223], v[248:251], v[40:43]
	v_mfma_f32_16x16x32_bf16 v[36:39], v[224:227], v[248:251], v[52:55]
	v_mfma_f32_16x16x32_bf16 v[32:35], v[228:231], v[248:251], v[32:35]
	v_div_scale_f32 v48, s[26:27], v142, v142, 1.0
	v_rcp_f32_e32 v49, v48
	s_nop 0
	v_fma_f32 v50, -v48, v49, 1.0
	v_fmac_f32_e32 v49, v50, v49
	v_div_scale_f32 v50, vcc, 1.0, v142, 1.0
	v_mul_f32_e32 v51, v50, v49
	v_fma_f32 v52, -v48, v51, v50
	v_fmac_f32_e32 v51, v52, v49
	v_fma_f32 v48, -v48, v51, v50
	v_div_fmas_f32 v48, v48, v49, v51
	v_div_fixup_f32 v52, v48, v142, 1.0
	v_lshlrev_b32_e32 v48, 1, v76
	v_mov_b32_e32 v49, v73
	v_lshl_add_u64 v[50:51], v[84:85], 0, v[48:49]
	v_mul_f32_e32 v44, v52, v44
	v_mul_f32_e32 v45, v52, v45
	v_mul_f32_e32 v46, v52, v46
	v_mul_f32_e32 v47, v52, v47
	v_lshlrev_b64 v[48:49], 11, v[82:83]
	v_lshl_add_u64 v[48:49], v[80:81], 0, v[48:49]
	v_mul_f32_e32 v41, v52, v41
	v_mul_f32_e32 v40, v52, v40
	v_mul_f32_e32 v42, v52, v42
	v_mul_f32_e32 v43, v52, v43
	v_mul_f32_e32 v37, v52, v37
	v_mul_f32_e32 v36, v52, v36
	v_mul_f32_e32 v38, v52, v38
	v_mul_f32_e32 v39, v52, v39
	v_mul_f32_e32 v33, v52, v33
	v_mul_f32_e32 v32, v52, v32
	v_mul_f32_e32 v34, v52, v34
	v_mul_f32_e32 v35, v52, v35
	s_waitcnt vmcnt(0)
; __device__ __forceinline__ unsigned cvt_pk_bf16(float lo, float hi) { unsigned r; asm volatile("v_cvt_pk_bf16_f32 %0, %1, %2" : "=v"(r) : "v"(lo), "v"(hi)); return r; }
; __device__ __forceinline__ float bflo(unsigned w) { return __uint_as_float(w << 16); }
; __device__ __forceinline__ float bfhi(unsigned w) { return __uint_as_float(w & 0xffff0000u); }
; __device__ __forceinline__ float fsigmoid(float x) { return __builtin_amdgcn_rcpf(1.0f + __expf(-x)); }
; __device__ __forceinline__ void attn_phase(LAS unsigned char* lds, const bf16_t* QKVZ, const float* sinks, bf16_t* OG, int G, int bid, int tid) {
;     ...
;             const bf16_t* zp = QKVZ + row * ATT_IN + 1536 + h * 64 + 4 * fq;
;             bf16_t* op = OG + row * D + h * 64 + 4 * fq;
; #pragma unroll
;             for (int dt = 0; dt < 4; ++dt) {
;                 const u32x2 zw = *(const u32x2*)(zp + dt * 16);
;                 const float z0 = bflo(zw.x), z1 = bfhi(zw.x), z2 = bflo(zw.y), z3 = bfhi(zw.y);
;                 const float r0 = o[dt][0] * inv * z0 * fsigmoid(z0), r1 = o[dt][1] * inv * z1 * fsigmoid(z1), r2 = o[dt][2] * inv * z2 * fsigmoid(z2), r3 = o[dt][3] * inv * z3 * fsigmoid(z3);
;                 u32x2 w; w.x = cvt_pk_bf16(r0, r1); w.y = cvt_pk_bf16(r2, r3);
;                 *(u32x2*)(op + dt * 16) = w;
;             }
	v_mov_b64_e32 v[54:55], v[200:201]
	v_lshlrev_b32_e32 v53, 16, v54
	v_mul_f32_e32 v44, v44, v53
	v_mul_f32_e32 v53, 0xbfb8aa3b, v53
	v_exp_f32_e32 v53, v53
	v_and_b32_e32 v54, 0xffff0000, v54
	v_lshlrev_b32_e32 v56, 16, v55
	v_mul_f32_e32 v45, v45, v54
	v_add_f32_e32 v53, 1.0, v53
	v_rcp_f32_e32 v53, v53
	v_and_b32_e32 v55, 0xffff0000, v55
	v_mul_f32_e32 v46, v46, v56
	v_mul_f32_e32 v47, v47, v55
	v_mul_f32_e32 v44, v44, v53
	v_mul_f32_e32 v53, 0xbfb8aa3b, v54
	v_exp_f32_e32 v53, v53
	s_nop 0
	v_add_f32_e32 v53, 1.0, v53
	v_rcp_f32_e32 v53, v53
	s_nop 0
	v_mul_f32_e32 v45, v45, v53
	v_mul_f32_e32 v53, 0xbfb8aa3b, v56
	v_exp_f32_e32 v53, v53
	v_cvt_pk_bf16_f32 v44, v44, v45
	s_nop 0
	v_add_f32_e32 v53, 1.0, v53
	v_rcp_f32_e32 v53, v53
	s_nop 0
	v_mul_f32_e32 v46, v46, v53
	v_mul_f32_e32 v53, 0xbfb8aa3b, v55
	v_exp_f32_e32 v53, v53
	s_nop 0
	v_add_f32_e32 v53, 1.0, v53
	v_rcp_f32_e32 v53, v53
	s_nop 0
	v_mul_f32_e32 v47, v47, v53
	v_cvt_pk_bf16_f32 v45, v46, v47
	global_store_dwordx2 v[48:49], v[44:45], off
	s_nop 1
	v_mov_b64_e32 v[44:45], v[202:203]
	v_lshlrev_b32_e32 v46, 16, v44
	v_and_b32_e32 v44, 0xffff0000, v44
	v_mul_f32_e32 v41, v41, v44
	v_mul_f32_e32 v44, 0xbfb8aa3b, v44
	v_exp_f32_e32 v44, v44
	v_lshlrev_b32_e32 v47, 16, v45
	v_and_b32_e32 v45, 0xffff0000, v45
	v_mul_f32_e32 v40, v40, v46
	v_add_f32_e32 v44, 1.0, v44
	v_rcp_f32_e32 v44, v44
	v_mul_f32_e32 v46, 0xbfb8aa3b, v46
	v_mul_f32_e32 v42, v42, v47
	v_exp_f32_e32 v46, v46
	v_mul_f32_e32 v41, v41, v44
	v_mul_f32_e32 v44, 0xbfb8aa3b, v47
	v_exp_f32_e32 v44, v44
	v_add_f32_e32 v46, 1.0, v46
	v_rcp_f32_e32 v46, v46
	v_mul_f32_e32 v43, v43, v45
	v_add_f32_e32 v44, 1.0, v44
	v_rcp_f32_e32 v44, v44
	v_mul_f32_e32 v40, v40, v46
	v_cvt_pk_bf16_f32 v40, v40, v41
	v_mul_f32_e32 v42, v42, v44
	v_mul_f32_e32 v44, 0xbfb8aa3b, v45
	v_exp_f32_e32 v44, v44
	s_nop 0
	v_add_f32_e32 v44, 1.0, v44
	v_rcp_f32_e32 v44, v44
	s_nop 0
	v_mul_f32_e32 v43, v43, v44
	v_cvt_pk_bf16_f32 v41, v42, v43
	global_store_dwordx2 v[48:49], v[40:41], off offset:32
	s_nop 1
	v_mov_b64_e32 v[40:41], v[204:205]
	v_lshlrev_b32_e32 v42, 16, v40
	v_and_b32_e32 v40, 0xffff0000, v40
	v_mul_f32_e32 v37, v37, v40
	v_mul_f32_e32 v40, 0xbfb8aa3b, v40
	v_exp_f32_e32 v40, v40
	v_lshlrev_b32_e32 v43, 16, v41
	v_and_b32_e32 v41, 0xffff0000, v41
	v_mul_f32_e32 v36, v36, v42
	v_add_f32_e32 v40, 1.0, v40
	v_rcp_f32_e32 v40, v40
	v_mul_f32_e32 v42, 0xbfb8aa3b, v42
	v_mul_f32_e32 v38, v38, v43
	v_exp_f32_e32 v42, v42
	v_mul_f32_e32 v37, v37, v40
	v_mul_f32_e32 v40, 0xbfb8aa3b, v43
	v_exp_f32_e32 v40, v40
	v_add_f32_e32 v42, 1.0, v42
	v_rcp_f32_e32 v42, v42
	v_mul_f32_e32 v39, v39, v41
	v_add_f32_e32 v40, 1.0, v40
	v_rcp_f32_e32 v40, v40
	v_mul_f32_e32 v36, v36, v42
	v_cvt_pk_bf16_f32 v36, v36, v37
	v_mul_f32_e32 v38, v38, v40
	v_mul_f32_e32 v40, 0xbfb8aa3b, v41
	v_exp_f32_e32 v40, v40
	s_nop 0
	v_add_f32_e32 v40, 1.0, v40
	v_rcp_f32_e32 v40, v40
	s_nop 0
	v_mul_f32_e32 v39, v39, v40
	v_cvt_pk_bf16_f32 v37, v38, v39
	global_store_dwordx2 v[48:49], v[36:37], off offset:64
	s_nop 1
	v_mov_b64_e32 v[36:37], v[206:207]
	v_lshlrev_b32_e32 v38, 16, v36
	v_and_b32_e32 v36, 0xffff0000, v36
	v_mul_f32_e32 v33, v33, v36
	v_mul_f32_e32 v36, 0xbfb8aa3b, v36
	v_exp_f32_e32 v36, v36
	v_lshlrev_b32_e32 v39, 16, v37
	v_and_b32_e32 v37, 0xffff0000, v37
	v_mul_f32_e32 v32, v32, v38
	v_add_f32_e32 v36, 1.0, v36
	v_rcp_f32_e32 v36, v36
	v_mul_f32_e32 v38, 0xbfb8aa3b, v38
	v_mul_f32_e32 v34, v34, v39
	v_exp_f32_e32 v38, v38
	v_mul_f32_e32 v33, v33, v36
	v_mul_f32_e32 v36, 0xbfb8aa3b, v39
	v_exp_f32_e32 v36, v36
	v_add_f32_e32 v38, 1.0, v38
	v_rcp_f32_e32 v38, v38
	v_mul_f32_e32 v35, v35, v37
	v_add_f32_e32 v36, 1.0, v36
	v_rcp_f32_e32 v36, v36
	v_mul_f32_e32 v32, v32, v38
	v_cvt_pk_bf16_f32 v32, v32, v33
	v_mul_f32_e32 v34, v34, v36
	v_mul_f32_e32 v36, 0xbfb8aa3b, v37
	v_exp_f32_e32 v36, v36
	s_nop 0
	v_add_f32_e32 v36, 1.0, v36
	v_rcp_f32_e32 v36, v36
	s_nop 0
	v_mul_f32_e32 v35, v35, v36
	v_cvt_pk_bf16_f32 v33, v34, v35
	global_store_dwordx2 v[48:49], v[32:33], off offset:96
	s_cbranch_scc0 .LBB0_246
	s_add_i32 s16, s16, s21
	s_and_b64 vcc, exec, s[10:11]
	s_mov_b32 s12, s24
	s_cbranch_vccz .LBB0_235
